# attention PV/QK LDS-read batching + fused late path, coalesced swizzled K image, batched unit epilogue, add-tree l-sum; gMLP second-buffer forced waits removed; final RMSNorm loop software-pipelined
# baseline (speedup 1.0000x reference)
.LBB13_816:
	s_or_b64 exec, exec, s[28:29]
	s_add_i32 s29, s30, s41
	s_cmp_ge_i32 s29, s33
	s_cbranch_scc1 .LBB13_826
	s_and_b32 s28, s29, 7
	s_cmp_eq_u32 s28, s39
	s_cbranch_scc1 .LBB13_819
	v_lshl_add_u32 v2, s28, 7, v76
	v_ashrrev_i32_e32 v3, 31, v2
	v_lshlrev_b64 v[20:21], 8, v[2:3]
	v_lshl_add_u64 v[32:33], v[78:79], 0, v[20:21]
	v_lshl_add_u64 v[2:3], v[2:3], 2, s[2:3]
	s_lshl_b32 s84, s28, 8
	global_load_dwordx4 v[20:23], v[32:33], off
	global_load_dwordx4 v[24:27], v[32:33], off offset:64
	global_load_dwordx4 v[28:31], v[32:33], off offset:128
	s_nop 0
	global_load_dwordx4 v[32:35], v[32:33], off offset:192
	s_mov_b32 s39, s28
	global_load_dword v88, v[2:3], off
	v_lshl_add_u64 v[2:3], v[82:83], 0, s[84:85]
	global_load_dwordx4 v[36:39], v[2:3], off
	global_load_dwordx4 v[40:43], v[2:3], off offset:64
	global_load_dwordx4 v[44:47], v[2:3], off offset:128
	global_load_dwordx4 v[48:51], v[2:3], off offset:192
	s_waitcnt vmcnt(0)

.LBB13_821:
	s_and_b64 vcc, exec, s[8:9]
	s_cbranch_vccnz .LBB13_827
	ds_read_b64_tr_b16 v[52:53], v128
	ds_read_b64_tr_b16 v[54:55], v129 offset:512
	ds_read_b64_tr_b16 v[56:57], v126
	ds_read_b64_tr_b16 v[58:59], v127 offset:512
	s_waitcnt lgkmcnt(2)
	v_mfma_f32_16x16x32_bf16 v[64:67], v[52:55], v[20:23], 0
	ds_read_b64_tr_b16 v[52:53], v124
	ds_read_b64_tr_b16 v[54:55], v125 offset:512
	ds_read_b64_tr_b16 v[106:107], v122
	ds_read_b64_tr_b16 v[108:109], v123 offset:512
	s_waitcnt lgkmcnt(4)
	v_mfma_f32_16x16x32_bf16 v[60:63], v[56:59], v[20:23], 0
	s_waitcnt lgkmcnt(2)
	v_mfma_f32_16x16x32_bf16 v[56:59], v[52:55], v[20:23], 0
	s_waitcnt lgkmcnt(0)
	v_mfma_f32_16x16x32_bf16 v[52:55], v[106:109], v[20:23], 0
	s_and_b64 vcc, exec, s[10:11]
	s_cbranch_vccz .LBB13_828
	s_branch .LBB13_829

.LBB13_828:
	ds_read_b64_tr_b16 v[106:107], v128 offset:4096
	ds_read_b64_tr_b16 v[108:109], v129 offset:4608
	ds_read_b64_tr_b16 v[130:131], v126 offset:4096
	ds_read_b64_tr_b16 v[132:133], v127 offset:4608
	s_waitcnt lgkmcnt(2)
	v_mfma_f32_16x16x32_bf16 v[64:67], v[106:109], v[24:27], v[64:67]
	ds_read_b64_tr_b16 v[106:107], v124 offset:4096
	ds_read_b64_tr_b16 v[108:109], v125 offset:4608
	s_waitcnt lgkmcnt(2)
	v_mfma_f32_16x16x32_bf16 v[60:63], v[130:133], v[24:27], v[60:63]
	ds_read_b64_tr_b16 v[130:131], v122 offset:4096
	ds_read_b64_tr_b16 v[132:133], v123 offset:4608
	s_waitcnt lgkmcnt(2)
	v_mfma_f32_16x16x32_bf16 v[56:59], v[106:109], v[24:27], v[56:59]
	s_waitcnt lgkmcnt(0)
	v_mfma_f32_16x16x32_bf16 v[52:55], v[130:133], v[24:27], v[52:55]

.LBB13_831:
	ds_read_b64_tr_b16 v[106:107], v128 offset:12288
	ds_read_b64_tr_b16 v[108:109], v129 offset:12800
	ds_read_b64_tr_b16 v[128:129], v126 offset:12288
	ds_read_b64_tr_b16 v[130:131], v127 offset:12800
	s_waitcnt lgkmcnt(2)
	v_mfma_f32_16x16x32_bf16 v[64:67], v[106:109], v[32:35], v[64:67]
	ds_read_b64_tr_b16 v[106:107], v124 offset:12288
	ds_read_b64_tr_b16 v[108:109], v125 offset:12800
	ds_read_b64_tr_b16 v[124:125], v122 offset:12288
	ds_read_b64_tr_b16 v[126:127], v123 offset:12800
	s_waitcnt lgkmcnt(4)
	v_mfma_f32_16x16x32_bf16 v[60:63], v[128:131], v[32:35], v[60:63]
	s_waitcnt lgkmcnt(2)
	v_mfma_f32_16x16x32_bf16 v[56:59], v[106:109], v[32:35], v[56:59]
	s_waitcnt lgkmcnt(0)
	v_mfma_f32_16x16x32_bf16 v[52:55], v[124:127], v[32:35], v[52:55]
.LBB13_832:
	s_ashr_i32 s8, s29, 3
	s_add_i32 s8, s8, s31
	s_ashr_i32 s9, s8, 31
	s_lshl_b64 s[8:9], s[8:9], 7
	v_lshl_add_u64 v[2:3], s[8:9], 0, v[76:77]
	v_lshlrev_b32_e32 v108, 16, v94
	v_and_b32_e32 v109, 0xffff0000, v94
	s_nop 0
	v_pk_add_f32 v[64:65], v[88:89], v[64:65] op_sel_hi:[0,1]
	v_lshlrev_b32_e32 v94, 16, v95
	v_and_b32_e32 v95, 0xffff0000, v95
	v_pk_add_f32 v[66:67], v[88:89], v[66:67] op_sel_hi:[0,1]
	v_lshlrev_b64 v[106:107], 12, v[2:3]
	v_pk_mul_f32 v[64:65], v[64:65], v[108:109]
	v_pk_mul_f32 v[66:67], v[66:67], v[94:95]
	v_lshl_add_u64 v[106:107], s[4:5], 0, v[106:107]
	v_pk_mul_f32 v[94:95], v[64:65], v[64:65]
	v_pk_mul_f32 v[108:109], v[66:67], v[66:67]
	s_nop 0
	v_pk_mul_f32 v[66:67], v[38:39], v[66:67]
	v_pk_mul_f32 v[64:65], v[36:37], v[64:65]
	v_lshl_or_b32 v0, s28, 7, v104
	v_cvt_pk_bf16_f32 v64, v64, v65
	v_cvt_pk_bf16_f32 v65, v66, v67
	v_lshl_add_u64 v[66:67], v[106:107], 0, v[0:1]
	global_store_dwordx2 v[66:67], v[64:65], off
	v_lshlrev_b32_e32 v64, 16, v92
	v_and_b32_e32 v65, 0xffff0000, v92
	v_pk_add_f32 v[60:61], v[88:89], v[60:61] op_sel_hi:[0,1]
	v_pk_mul_f32 v[60:61], v[60:61], v[64:65]
	v_lshlrev_b32_e32 v64, 16, v93
	v_and_b32_e32 v65, 0xffff0000, v93
	v_pk_add_f32 v[62:63], v[88:89], v[62:63] op_sel_hi:[0,1]
	v_pk_mul_f32 v[62:63], v[62:63], v[64:65]
	v_pk_mul_f32 v[64:65], v[60:61], v[60:61]
	s_nop 0
	v_pk_mul_f32 v[60:61], v[40:41], v[60:61]
	v_pk_mul_f32 v[92:93], v[62:63], v[62:63]
	v_pk_mul_f32 v[62:63], v[42:43], v[62:63]
	v_cvt_pk_bf16_f32 v60, v60, v61
	v_pk_add_f32 v[56:57], v[88:89], v[56:57] op_sel_hi:[0,1]
	v_cvt_pk_bf16_f32 v61, v62, v63
	global_store_dwordx2 v[66:67], v[60:61], off offset:32
	v_lshlrev_b32_e32 v60, 16, v90
	v_and_b32_e32 v61, 0xffff0000, v90
	v_pk_mul_f32 v[56:57], v[56:57], v[60:61]
	v_lshlrev_b32_e32 v60, 16, v91
	v_and_b32_e32 v61, 0xffff0000, v91
	v_pk_add_f32 v[58:59], v[88:89], v[58:59] op_sel_hi:[0,1]
	v_pk_mul_f32 v[58:59], v[58:59], v[60:61]
	v_pk_mul_f32 v[60:61], v[56:57], v[56:57]
	s_nop 0
	v_pk_mul_f32 v[56:57], v[44:45], v[56:57]
	v_pk_mul_f32 v[62:63], v[58:59], v[58:59]
	v_pk_mul_f32 v[58:59], v[46:47], v[58:59]
	v_cvt_pk_bf16_f32 v56, v56, v57
	v_pk_add_f32 v[52:53], v[88:89], v[52:53] op_sel_hi:[0,1]
	v_cvt_pk_bf16_f32 v57, v58, v59
	global_store_dwordx2 v[66:67], v[56:57], off offset:64
	v_lshlrev_b32_e32 v56, 16, v86
	v_and_b32_e32 v57, 0xffff0000, v86
	v_pk_mul_f32 v[52:53], v[52:53], v[56:57]
	v_lshlrev_b32_e32 v56, 16, v87
	v_and_b32_e32 v57, 0xffff0000, v87
	v_pk_add_f32 v[54:55], v[88:89], v[54:55] op_sel_hi:[0,1]
	v_add_f32_e32 v0, v108, v109
	v_add_f32_e32 v86, v94, v95
	v_pk_mul_f32 v[54:55], v[54:55], v[56:57]
	v_add_f32_e32 v0, v86, v0
	v_add_f32_e32 v86, v92, v93
	v_add_f32_e32 v64, v64, v65
	v_pk_mul_f32 v[56:57], v[52:53], v[52:53]
	v_pk_mul_f32 v[58:59], v[54:55], v[54:55]
	v_add_f32_e32 v64, v64, v86
	v_add_f32_e32 v62, v62, v63
	v_add_f32_e32 v60, v60, v61
	v_add_f32_e32 v0, v64, v0
	v_add_f32_e32 v60, v60, v62
	v_add_f32_e32 v58, v58, v59
	v_add_f32_e32 v56, v56, v57
	v_add_f32_e32 v0, v60, v0
	v_add_f32_e32 v56, v56, v58
	v_add_f32_e32 v0, v56, v0
	ds_swizzle_b32 v56, v0 offset:swizzle(SWAP,16)
	s_nop 0
	v_pk_mul_f32 v[52:53], v[48:49], v[52:53]
	v_pk_mul_f32 v[54:55], v[50:51], v[54:55]
	v_cvt_pk_bf16_f32 v52, v52, v53
	s_waitcnt lgkmcnt(0)
	v_add_f32_e32 v0, v0, v56
	v_cvt_pk_bf16_f32 v53, v54, v55
	global_store_dwordx2 v[66:67], v[52:53], off offset:96
	v_mov_b32_e32 v52, v0
	s_nop 1
	v_permlane32_swap_b32_e32 v0, v52
	s_and_saveexec_b64 s[8:9], s[6:7]
	s_cbranch_execz .LBB13_803
	v_lshlrev_b64 v[2:3], 6, v[2:3]
	v_lshl_add_u64 v[2:3], s[16:17], 0, v[2:3]
	s_lshl_b32 s84, s28, 2
	v_lshl_add_u64 v[2:3], v[2:3], 0, s[84:85]
	v_add_f32_e32 v0, v0, v52
	global_store_dword v[2:3], v0, off
	s_branch .LBB13_803
.LBB13_834:
	ds_read_b64_tr_b16 v[106:107], v128 offset:8192
	ds_read_b64_tr_b16 v[108:109], v129 offset:8704
	ds_read_b64_tr_b16 v[130:131], v126 offset:8192
	ds_read_b64_tr_b16 v[132:133], v127 offset:8704
	s_waitcnt lgkmcnt(2)
	v_mfma_f32_16x16x32_bf16 v[64:67], v[106:109], v[28:31], v[64:67]
	ds_read_b64_tr_b16 v[106:107], v124 offset:8192
	ds_read_b64_tr_b16 v[108:109], v125 offset:8704
	s_waitcnt lgkmcnt(2)
	v_mfma_f32_16x16x32_bf16 v[60:63], v[130:133], v[28:31], v[60:63]
	ds_read_b64_tr_b16 v[130:131], v122 offset:8192
	ds_read_b64_tr_b16 v[132:133], v123 offset:8704
	s_waitcnt lgkmcnt(2)
	v_mfma_f32_16x16x32_bf16 v[56:59], v[106:109], v[28:31], v[56:59]
	s_waitcnt lgkmcnt(0)
	v_mfma_f32_16x16x32_bf16 v[52:55], v[130:133], v[28:31], v[52:55]
	s_and_b64 vcc, exec, s[14:15]
	s_cbranch_vccz .LBB13_831
	s_branch .LBB13_832

.LBB13_1794:
	s_or_b64 exec, exec, s[28:29]
	s_add_i32 s29, s30, s41
	s_cmp_ge_i32 s29, s33
	s_cbranch_scc1 .LBB13_1804
	s_and_b32 s28, s29, 7
	s_cmp_eq_u32 s28, s39
	s_cbranch_scc1 .LBB13_1797
	v_lshl_add_u32 v2, s28, 7, v76
	v_ashrrev_i32_e32 v3, 31, v2
	v_lshlrev_b64 v[20:21], 8, v[2:3]
	v_lshl_add_u64 v[32:33], v[78:79], 0, v[20:21]
	v_lshl_add_u64 v[2:3], v[2:3], 2, s[4:5]
	s_lshl_b32 s84, s28, 8
	global_load_dwordx4 v[20:23], v[32:33], off
	global_load_dwordx4 v[24:27], v[32:33], off offset:64
	global_load_dwordx4 v[28:31], v[32:33], off offset:128
	s_nop 0
	global_load_dwordx4 v[32:35], v[32:33], off offset:192
	s_mov_b32 s39, s28
	global_load_dword v88, v[2:3], off
	v_lshl_add_u64 v[2:3], v[82:83], 0, s[84:85]
	global_load_dwordx4 v[36:39], v[2:3], off offset:2048
	global_load_dwordx4 v[40:43], v[2:3], off offset:2112
	global_load_dwordx4 v[44:47], v[2:3], off offset:2176
	global_load_dwordx4 v[48:51], v[2:3], off offset:2240
	s_waitcnt vmcnt(0)

.LBB13_1810:
	s_ashr_i32 s8, s29, 3
	s_add_i32 s8, s8, s31
	s_ashr_i32 s9, s8, 31
	s_lshl_b64 s[8:9], s[8:9], 7
	v_lshl_add_u64 v[2:3], s[8:9], 0, v[76:77]
	v_lshlrev_b32_e32 v108, 16, v94
	v_and_b32_e32 v109, 0xffff0000, v94
	s_nop 0
	v_pk_add_f32 v[64:65], v[88:89], v[64:65] op_sel_hi:[0,1]
	v_lshlrev_b32_e32 v94, 16, v95
	v_and_b32_e32 v95, 0xffff0000, v95
	v_pk_add_f32 v[66:67], v[88:89], v[66:67] op_sel_hi:[0,1]
	v_lshlrev_b64 v[106:107], 12, v[2:3]
	v_pk_mul_f32 v[64:65], v[64:65], v[108:109]
	v_pk_mul_f32 v[66:67], v[66:67], v[94:95]
	v_lshl_add_u64 v[106:107], s[2:3], 0, v[106:107]
	v_pk_mul_f32 v[94:95], v[64:65], v[64:65]
	v_pk_mul_f32 v[108:109], v[66:67], v[66:67]
	s_nop 0
	v_pk_mul_f32 v[66:67], v[38:39], v[66:67]
	v_pk_mul_f32 v[64:65], v[36:37], v[64:65]
	v_lshl_or_b32 v0, s28, 7, v104
	v_cvt_pk_bf16_f32 v64, v64, v65
	v_cvt_pk_bf16_f32 v65, v66, v67
	v_lshl_add_u64 v[66:67], v[106:107], 0, v[0:1]
	global_store_dwordx2 v[66:67], v[64:65], off
	v_lshlrev_b32_e32 v64, 16, v92
	v_and_b32_e32 v65, 0xffff0000, v92
	v_pk_add_f32 v[60:61], v[88:89], v[60:61] op_sel_hi:[0,1]
	v_pk_mul_f32 v[60:61], v[60:61], v[64:65]
	v_lshlrev_b32_e32 v64, 16, v93
	v_and_b32_e32 v65, 0xffff0000, v93
	v_pk_add_f32 v[62:63], v[88:89], v[62:63] op_sel_hi:[0,1]
	v_pk_mul_f32 v[62:63], v[62:63], v[64:65]
	v_pk_mul_f32 v[64:65], v[60:61], v[60:61]
	s_nop 0
	v_pk_mul_f32 v[60:61], v[40:41], v[60:61]
	v_pk_mul_f32 v[92:93], v[62:63], v[62:63]
	v_pk_mul_f32 v[62:63], v[42:43], v[62:63]
	v_cvt_pk_bf16_f32 v60, v60, v61
	v_pk_add_f32 v[56:57], v[88:89], v[56:57] op_sel_hi:[0,1]
	v_cvt_pk_bf16_f32 v61, v62, v63
	global_store_dwordx2 v[66:67], v[60:61], off offset:32
	v_lshlrev_b32_e32 v60, 16, v90
	v_and_b32_e32 v61, 0xffff0000, v90
	v_pk_mul_f32 v[56:57], v[56:57], v[60:61]
	v_lshlrev_b32_e32 v60, 16, v91
	v_and_b32_e32 v61, 0xffff0000, v91
	v_pk_add_f32 v[58:59], v[88:89], v[58:59] op_sel_hi:[0,1]
	v_pk_mul_f32 v[58:59], v[58:59], v[60:61]
	v_pk_mul_f32 v[60:61], v[56:57], v[56:57]
	s_nop 0
	v_pk_mul_f32 v[56:57], v[44:45], v[56:57]
	v_pk_mul_f32 v[62:63], v[58:59], v[58:59]
	v_pk_mul_f32 v[58:59], v[46:47], v[58:59]
	v_cvt_pk_bf16_f32 v56, v56, v57
	v_pk_add_f32 v[52:53], v[88:89], v[52:53] op_sel_hi:[0,1]
	v_cvt_pk_bf16_f32 v57, v58, v59
	global_store_dwordx2 v[66:67], v[56:57], off offset:64
	v_lshlrev_b32_e32 v56, 16, v86
	v_and_b32_e32 v57, 0xffff0000, v86
	v_pk_mul_f32 v[52:53], v[52:53], v[56:57]
	v_lshlrev_b32_e32 v56, 16, v87
	v_and_b32_e32 v57, 0xffff0000, v87
	v_pk_add_f32 v[54:55], v[88:89], v[54:55] op_sel_hi:[0,1]
	v_add_f32_e32 v0, v108, v109
	v_add_f32_e32 v86, v94, v95
	v_pk_mul_f32 v[54:55], v[54:55], v[56:57]
	v_add_f32_e32 v0, v86, v0
	v_add_f32_e32 v86, v92, v93
	v_add_f32_e32 v64, v64, v65
	v_pk_mul_f32 v[56:57], v[52:53], v[52:53]
	v_pk_mul_f32 v[58:59], v[54:55], v[54:55]
	v_add_f32_e32 v64, v64, v86
	v_add_f32_e32 v62, v62, v63
	v_add_f32_e32 v60, v60, v61
	v_add_f32_e32 v0, v64, v0
	v_add_f32_e32 v60, v60, v62
	v_add_f32_e32 v58, v58, v59
	v_add_f32_e32 v56, v56, v57
	v_add_f32_e32 v0, v60, v0
	v_add_f32_e32 v56, v56, v58
	v_add_f32_e32 v0, v56, v0
	ds_swizzle_b32 v56, v0 offset:swizzle(SWAP,16)
	s_nop 0
	v_pk_mul_f32 v[52:53], v[48:49], v[52:53]
	v_pk_mul_f32 v[54:55], v[50:51], v[54:55]
	v_cvt_pk_bf16_f32 v52, v52, v53
	s_waitcnt lgkmcnt(0)
	v_add_f32_e32 v0, v0, v56
	v_cvt_pk_bf16_f32 v53, v54, v55
	global_store_dwordx2 v[66:67], v[52:53], off offset:96
	v_mov_b32_e32 v52, v0
	s_nop 1
	v_permlane32_swap_b32_e32 v0, v52
	s_and_saveexec_b64 s[8:9], s[6:7]
	s_cbranch_execz .LBB13_1781
	v_lshlrev_b64 v[2:3], 6, v[2:3]
	v_lshl_add_u64 v[2:3], s[16:17], 0, v[2:3]
	s_lshl_b32 s84, s28, 2
	v_lshl_add_u64 v[2:3], v[2:3], 0, s[84:85]
	v_add_f32_e32 v0, v0, v52
	global_store_dword v[2:3], v0, off
	s_branch .LBB13_1781

; __device__ __forceinline__ int lane_id() { int l; asm volatile("v_mbcnt_lo_u32_b32 %0, -1, 0\n\tv_mbcnt_hi_u32_b32 %0, -1, %0" : "=v"(l)); return l; }
; __device__ __forceinline__ float hsq4(const f32x4& a) { return (a[0] * a[0] + a[1] * a[1]) + (a[2] * a[2] + a[3] * a[3]); }
; __device__ __forceinline__ void phase_final(int wid0, const pg8::Place& pl, const float* g, const bf16_t* xb, float* dst) {
;     int tid_ = wid0 * 64 + lane_id(); asm volatile("" : "+v"(tid_));
;     const int lane = tid_ & 63, wave = tid_ >> 6, nr = T / pl.nx, r0 = pl.jx * nr;
;     for (int lr = pl.rank * NWAVES + wave; lr < nr; lr += pl.nloc * NWAVES) { const int row = r0 + lr;
;         const pg8::u32x2* xr = (const pg8::u32x2*)(xb + (size_t)row * (2 * DM) + DM); f32x4* yr = (f32x4*)(dst + (size_t)row * DM); f32x4 v[4]; float s = 0.f;
; #pragma unroll
;         for (int j = 0; j < 4; ++j) { const pg8::u32x2 w = xr[lane + 64 * j];
;             v[j][0] = __uint_as_float(w.x << 16); v[j][1] = __uint_as_float(w.x & 0xffff0000u); v[j][2] = __uint_as_float(w.y << 16); v[j][3] = __uint_as_float(w.y & 0xffff0000u); s += pg8::hsq4(v[j]); }
;         const float rstd = rsqrtf(wsum(s) * (1.f / DM) + EPS);
; #pragma unroll
;         for (int j = 0; j < 4; ++j) yr[lane + 64 * j] = v[j] * rstd * *(const f32x4*)(g + 4 * (lane + 64 * j)); }
; }
.LBB13_2253:
	global_load_dwordx4 v[44:47], v[0:1], off
	global_load_dwordx4 v[48:51], v[2:3], off
	global_load_dwordx4 v[52:55], v[4:5], off
	global_load_dwordx4 v[56:59], v[6:7], off
	v_lshl_add_u64 v[18:19], v[8:9], 0, s[2:3]
	global_load_dwordx2 v[60:61], v[18:19], off offset:2048
	global_load_dwordx2 v[62:63], v[18:19], off offset:2560
	global_load_dwordx2 v[64:65], v[18:19], off offset:3072
	global_load_dwordx2 v[66:67], v[18:19], off offset:3584
	s_waitcnt vmcnt(0)
	s_branch .Lfin_body
.Lfin_top:
	s_waitcnt vmcnt(4)
.Lfin_body:
	v_mov_b32_e32 v20, v60
	v_mov_b32_e32 v21, v61
	v_mov_b32_e32 v22, v62
	v_mov_b32_e32 v23, v63
	v_mov_b32_e32 v24, v64
	v_mov_b32_e32 v25, v65
	v_mov_b32_e32 v26, v66
	v_mov_b32_e32 v27, v67
	v_lshl_add_u64 v[18:19], v[10:11], 0, s[2:3]
	v_add_u32_e32 v12, s0, v12
	v_lshl_add_u64 v[8:9], v[8:9], 0, s[4:5]
	v_lshl_add_u64 v[10:11], v[10:11], 0, s[4:5]
	v_cmp_le_i32_e32 vcc, s8, v12
	s_or_b64 s[6:7], vcc, s[6:7]
	s_cbranch_vccnz .Lfin_noload
	v_lshl_add_u64 v[72:73], v[8:9], 0, s[2:3]
	global_load_dwordx2 v[60:61], v[72:73], off offset:2048
	global_load_dwordx2 v[62:63], v[72:73], off offset:2560
	global_load_dwordx2 v[64:65], v[72:73], off offset:3072
	global_load_dwordx2 v[66:67], v[72:73], off offset:3584
.Lfin_noload:
	v_lshlrev_b32_e32 v28, 16, v20
	v_and_b32_e32 v29, 0xffff0000, v20
	v_lshlrev_b32_e32 v20, 16, v21
	v_lshlrev_b32_e32 v30, 16, v22
	v_and_b32_e32 v31, 0xffff0000, v22
	v_lshlrev_b32_e32 v22, 16, v23
	v_and_b32_e32 v21, 0xffff0000, v21
	v_and_b32_e32 v23, 0xffff0000, v23
	v_lshlrev_b32_e32 v32, 16, v24
	v_and_b32_e32 v33, 0xffff0000, v24
	v_lshlrev_b32_e32 v24, 16, v25
	v_mul_f32_e32 v36, v29, v29
	v_mul_f32_e32 v37, v20, v20
	v_mul_f32_e32 v38, v31, v31
	v_mul_f32_e32 v39, v22, v22
	v_and_b32_e32 v25, 0xffff0000, v25
	v_lshlrev_b32_e32 v34, 16, v26
	v_and_b32_e32 v35, 0xffff0000, v26
	v_lshlrev_b32_e32 v26, 16, v27
	v_mul_f32_e32 v40, v33, v33
	v_mul_f32_e32 v41, v24, v24
	v_fmac_f32_e32 v36, v28, v28
	v_fmac_f32_e32 v37, v21, v21
	v_fmac_f32_e32 v38, v30, v30
	v_fmac_f32_e32 v39, v23, v23
	v_and_b32_e32 v27, 0xffff0000, v27
	v_mul_f32_e32 v42, v35, v35
	v_mul_f32_e32 v43, v26, v26
	v_fmac_f32_e32 v40, v32, v32
	v_fmac_f32_e32 v41, v25, v25
	v_add_f32_e32 v36, v36, v37
	v_add_f32_e32 v37, v38, v39
	v_fmac_f32_e32 v42, v34, v34
	v_fmac_f32_e32 v43, v27, v27
	v_add_f32_e32 v38, v40, v41
	v_add_f32_e32 v36, v36, v37
	v_add_f32_e32 v39, v42, v43
	v_add_f32_e32 v36, v36, v38
	v_add_f32_e32 v36, v36, v39
	ds_swizzle_b32 v37, v36 offset:swizzle(SWAP,1)
	s_waitcnt lgkmcnt(0)
	v_add_f32_e32 v36, v36, v37
	ds_swizzle_b32 v37, v36 offset:swizzle(SWAP,2)
	s_waitcnt lgkmcnt(0)
	v_add_f32_e32 v36, v36, v37
	ds_swizzle_b32 v37, v36 offset:swizzle(SWAP,4)
	s_waitcnt lgkmcnt(0)
	v_add_f32_e32 v36, v36, v37
	ds_swizzle_b32 v37, v36 offset:swizzle(SWAP,8)
	s_waitcnt lgkmcnt(0)
	v_add_f32_e32 v36, v36, v37
	ds_swizzle_b32 v37, v36 offset:swizzle(SWAP,16)
	s_waitcnt lgkmcnt(0)
	v_add_f32_e32 v36, v36, v37
	v_mov_b32_e32 v37, v36
	s_nop 1
	v_permlane32_swap_b32_e32 v36, v37
	v_add_f32_e32 v36, v36, v37
	v_fmamk_f32 v36, v36, 0x3a800000, v13
	v_mul_f32_e32 v37, 0x4b800000, v36
	v_cmp_gt_f32_e32 vcc, s1, v36
	s_nop 1
	v_cndmask_b32_e32 v36, v36, v37, vcc
	v_rsq_f32_e32 v36, v36
	s_nop 0
	v_mul_f32_e32 v37, 0x45800000, v36
	v_cndmask_b32_e32 v36, v36, v37, vcc
	v_pk_mul_f32 v[28:29], v[28:29], v[36:37] op_sel_hi:[1,0]
	v_pk_mul_f32 v[20:21], v[20:21], v[36:37] op_sel_hi:[1,0]
	v_pk_mul_f32 v[14:15], v[44:45], v[28:29]
	v_pk_mul_f32 v[16:17], v[46:47], v[20:21]
	global_store_dwordx4 v[18:19], v[14:17], off
	v_pk_mul_f32 v[20:21], v[22:23], v[36:37] op_sel_hi:[1,0]
	v_pk_mul_f32 v[22:23], v[30:31], v[36:37] op_sel_hi:[1,0]
	v_pk_mul_f32 v[68:69], v[48:49], v[22:23]
	v_pk_mul_f32 v[70:71], v[50:51], v[20:21]
	global_store_dwordx4 v[18:19], v[68:71], off offset:1024
	v_pk_mul_f32 v[20:21], v[24:25], v[36:37] op_sel_hi:[1,0]
	v_pk_mul_f32 v[22:23], v[32:33], v[36:37] op_sel_hi:[1,0]
	v_pk_mul_f32 v[16:17], v[54:55], v[20:21]
	v_pk_mul_f32 v[14:15], v[52:53], v[22:23]
	global_store_dwordx4 v[18:19], v[14:17], off offset:2048
	v_pk_mul_f32 v[20:21], v[26:27], v[36:37] op_sel_hi:[1,0]
	v_pk_mul_f32 v[22:23], v[34:35], v[36:37] op_sel_hi:[1,0]
	v_pk_mul_f32 v[70:71], v[58:59], v[20:21]
	v_pk_mul_f32 v[68:69], v[56:57], v[22:23]
	global_store_dwordx4 v[18:19], v[68:71], off offset:3072
	s_andn2_b64 exec, exec, s[6:7]
	s_cbranch_execnz .Lfin_top
